# v17
# baseline (speedup 1.0000x reference)
; __global__ void __launch_bounds__(512, 2) hymba_fwd(Params p) {
;     ...
;   phase_prep(p, lds);
;   grid.sync();
;   phase_inproj(p, lds);
.LBB0_37:
	s_or_b64 exec, exec, s[0:1]
	v_lshrrev_b32_e32 v1, 20, v0
	v_lshrrev_b32_e32 v0, 10, v0
	v_or_b32_e32 v0, v0, v1
	s_movk_i32 s0, 0x3ff
	v_and_or_b32 v0, v0, s0, v164
	s_waitcnt lgkmcnt(0)
	v_cmp_eq_u32_e64 s[58:59], 0, v0
	s_barrier
	s_and_saveexec_b64 s[0:1], s[58:59]
	s_cbranch_execz .LBB0_47
	buffer_wbl2 sc1
	s_waitcnt vmcnt(0)
	v_mov_b32_e32 v2, 0
	s_load_dwordx2 s[4:5], s[92:93], 0x58
	s_and_b32 s6, s2, 7
	s_mov_b32 s7, 1
	v_writelane_b32 v255, s7, 61
	s_nop 3
	s_lshl_b32 s6, s6, 6
	s_add_i32 s6, s6, 0x1f80800
	v_mov_b32_e32 v1, s6
	s_waitcnt lgkmcnt(0)
	v_writelane_b32 v255, s4, 58
	v_writelane_b32 v255, s5, 59
	global_load_dword v0, v2, s[4:5] offset:40
	global_load_dword v3, v2, s[4:5] offset:32 sc1
	s_waitcnt vmcnt(0)
	v_readfirstlane_b32 s6, v0
	s_nop 3
	v_writelane_b32 v255, s6, 60
	v_readfirstlane_b32 s6, v3
	s_nop 3
	s_and_b32 vcc_hi, s6, 0xffff0000
	v_mov_b32_e32 v3, 1
	global_atomic_add v3, v1, v3, s[90:91] sc0
	s_waitcnt vmcnt(0)
	v_readfirstlane_b32 s6, v0
	s_nop 3
	s_lshr_b32 vcc_lo, s6, 3
	s_mul_i32 s7, s7, vcc_lo
	v_readfirstlane_b32 s6, v3
	s_nop 3
	s_add_i32 s6, s6, 1
	s_cmp_eq_u32 s6, s7
	s_cbranch_scc0 .Lgb0_poll
	v_mov_b32_e32 v3, vcc_lo
	global_atomic_add v3, v2, v3, s[4:5] offset:32 sc0
	s_waitcnt vmcnt(0)
	v_readfirstlane_b32 s6, v3
	v_readfirstlane_b32 s7, v0
	s_nop 3
	s_and_b32 s6, s6, 0xffff
	s_add_i32 s6, s6, vcc_lo
	s_cmp_eq_u32 s6, s7
	s_cbranch_scc0 .Lgb0_poll
	s_sub_i32 s6, 0x10000, s7
	v_mov_b32_e32 v3, s6
	global_atomic_add v2, v3, s[4:5] offset:32

; __global__ void __launch_bounds__(512, 2) hymba_fwd(Params p) {
;     ...
;   phase_inproj(p, lds);
;   grid.sync();
;   phase_conv(p);
.LBB0_125:
	s_barrier
	s_and_saveexec_b64 s[0:1], s[58:59]
	s_cbranch_execz .LBB0_135
	buffer_wbl2 sc1
	s_waitcnt vmcnt(0)
	v_mov_b32_e32 v2, 0
	v_readlane_b32 s4, v255, 58
	v_readlane_b32 s5, v255, 59
	v_readlane_b32 s6, v255, 60
	v_readlane_b32 s7, v255, 61
	v_readlane_b32 vcc_hi, v255, 62
	s_nop 3
	v_mov_b32_e32 v0, s6
	v_readlane_b32 s6, v255, 2
	s_add_i32 s7, s7, 1
	v_writelane_b32 v255, s7, 61
	s_nop 3
	s_lshl_b32 s6, s6, 6
	s_add_i32 s6, s6, 0x1f80800
	v_mov_b32_e32 v1, s6
	v_mov_b32_e32 v3, 1
	global_atomic_add v3, v1, v3, s[90:91] sc0
	s_waitcnt vmcnt(0)
	v_readfirstlane_b32 s6, v0
	s_nop 3
	s_lshr_b32 vcc_lo, s6, 3
	s_mul_i32 s7, s7, vcc_lo
	v_readfirstlane_b32 s6, v3
	s_nop 3
	s_add_i32 s6, s6, 1
	s_cmp_eq_u32 s6, s7
	s_cbranch_scc0 .Lgb1_poll
	v_mov_b32_e32 v3, vcc_lo
	global_atomic_add v3, v2, v3, s[4:5] offset:32 sc0
	s_waitcnt vmcnt(0)
	v_readfirstlane_b32 s6, v3
	v_readfirstlane_b32 s7, v0
	s_nop 3
	s_and_b32 s6, s6, 0xffff
	s_add_i32 s6, s6, vcc_lo
	s_cmp_eq_u32 s6, s7
	s_cbranch_scc0 .Lgb1_poll
	s_sub_i32 s6, 0x10000, s7
	v_mov_b32_e32 v3, s6
	global_atomic_add v2, v3, s[4:5] offset:32

; __global__ void __launch_bounds__(512, 2) hymba_fwd(Params p) {
;     ...
;   phase_mix(p, lds);
;   grid.sync();
;   phase_ssmnorm(p);
.LBB0_279:
	s_barrier
	s_mov_b64 s[0:1], exec
	v_readlane_b32 s4, v255, 25
	v_readlane_b32 s68, v255, 20
	v_readlane_b32 s18, v255, 39
	v_readlane_b32 s19, v255, 40
	v_readlane_b32 s69, v255, 21
	v_readlane_b32 s6, v255, 27
	v_readlane_b32 s7, v255, 28
	v_readlane_b32 s10, v255, 31
	v_readlane_b32 s11, v255, 32
	v_readlane_b32 s16, v255, 37
	v_readlane_b32 s17, v255, 38
	s_mov_b64 s[62:63], s[18:19]
	v_readlane_b32 s66, v255, 22
	v_readlane_b32 s88, v255, 45
	s_and_b64 s[2:3], s[0:1], s[68:69]
	s_mov_b64 s[60:61], s[16:17]
	s_mov_b64 s[50:51], s[6:7]
	s_mov_b64 s[54:55], s[10:11]
	v_readlane_b32 s64, v255, 24
	v_readlane_b32 s67, v255, 23
	v_readlane_b32 s65, v255, 0
	v_readlane_b32 s70, v255, 1
	v_readlane_b32 s71, v255, 19
	v_readlane_b32 s89, v255, 46
	v_readlane_b32 s5, v255, 26
	v_readlane_b32 s8, v255, 29
	v_readlane_b32 s9, v255, 30
	v_readlane_b32 s12, v255, 33
	v_readlane_b32 s13, v255, 34
	v_readlane_b32 s14, v255, 35
	v_readlane_b32 s15, v255, 36
	s_mov_b64 exec, s[2:3]
	s_cbranch_execz .LBB0_289
	buffer_wbl2 sc1
	s_waitcnt vmcnt(0)
	v_mov_b32_e32 v2, 0
	v_readlane_b32 s4, v255, 58
	v_readlane_b32 s5, v255, 59
	v_readlane_b32 s6, v255, 60
	v_readlane_b32 s7, v255, 61
	v_readlane_b32 vcc_hi, v255, 62
	s_nop 3
	v_mov_b32_e32 v0, s6
	v_readlane_b32 s6, v255, 2
	s_add_i32 s7, s7, 1
	v_writelane_b32 v255, s7, 61
	s_nop 3
	s_lshl_b32 s6, s6, 6
	s_add_i32 s6, s6, 0x1f80800
	v_mov_b32_e32 v1, s6
	v_mov_b32_e32 v3, 1
	global_atomic_add v3, v1, v3, s[90:91] sc0
	s_waitcnt vmcnt(0)
	v_readfirstlane_b32 s6, v0
	s_nop 3
	s_lshr_b32 vcc_lo, s6, 3
	s_mul_i32 s7, s7, vcc_lo
	v_readfirstlane_b32 s6, v3
	s_nop 3
	s_add_i32 s6, s6, 1
	s_cmp_eq_u32 s6, s7
	s_cbranch_scc0 .Lgb3_poll
	v_mov_b32_e32 v3, vcc_lo
	global_atomic_add v3, v2, v3, s[4:5] offset:32 sc0
	s_waitcnt vmcnt(0)
	v_readfirstlane_b32 s6, v3
	v_readfirstlane_b32 s7, v0
	s_nop 3
	s_and_b32 s6, s6, 0xffff
	s_add_i32 s6, s6, vcc_lo
	s_cmp_eq_u32 s6, s7
	s_cbranch_scc0 .Lgb3_poll
	s_sub_i32 s6, 0x10000, s7
	v_mov_b32_e32 v3, s6
	global_atomic_add v2, v3, s[4:5] offset:32

; __global__ void __launch_bounds__(512, 2) hymba_fwd(Params p) {
;     ...
;   phase_ssmnorm(p);
;   grid.sync();
;   phase_outproj(p, lds);
.LBB0_300:
	s_or_b64 exec, exec, s[0:1]
	s_barrier
	s_and_saveexec_b64 s[0:1], s[68:69]
	v_readlane_b32 s51, v255, 2
	s_cbranch_execz .LBB0_310
	buffer_wbl2 sc1
	s_waitcnt vmcnt(0)
	v_mov_b32_e32 v2, 0
	v_readlane_b32 s4, v255, 58
	v_readlane_b32 s5, v255, 59
	v_readlane_b32 s6, v255, 60
	v_readlane_b32 s7, v255, 61
	v_readlane_b32 vcc_hi, v255, 62
	s_nop 3
	v_mov_b32_e32 v0, s6
	v_readlane_b32 s6, v255, 2
	s_add_i32 s7, s7, 1
	v_writelane_b32 v255, s7, 61
	s_nop 3
	s_lshl_b32 s6, s6, 6
	s_add_i32 s6, s6, 0x1f80800
	v_mov_b32_e32 v1, s6
	v_mov_b32_e32 v3, 1
	global_atomic_add v3, v1, v3, s[90:91] sc0
	s_waitcnt vmcnt(0)
	v_readfirstlane_b32 s6, v0
	s_nop 3
	s_lshr_b32 vcc_lo, s6, 3
	s_mul_i32 s7, s7, vcc_lo
	v_readfirstlane_b32 s6, v3
	s_nop 3
	s_add_i32 s6, s6, 1
	s_cmp_eq_u32 s6, s7
	s_cbranch_scc0 .Lgb4_poll
	v_mov_b32_e32 v3, vcc_lo
	global_atomic_add v3, v2, v3, s[4:5] offset:32 sc0
	s_waitcnt vmcnt(0)
	v_readfirstlane_b32 s6, v3
	v_readfirstlane_b32 s7, v0
	s_nop 3
	s_and_b32 s6, s6, 0xffff
	s_add_i32 s6, s6, vcc_lo
	s_cmp_eq_u32 s6, s7
	s_cbranch_scc0 .Lgb4_poll
	s_sub_i32 s6, 0x10000, s7
	v_mov_b32_e32 v3, s6
	global_atomic_add v2, v3, s[4:5] offset:32

; __global__ void __launch_bounds__(512, 2) hymba_fwd(Params p) {
;     ...
;   phase_outproj(p, lds);
;   grid.sync();
;   phase_norm2(p);
.LBB0_323:
	s_barrier
	s_and_saveexec_b64 s[2:3], s[68:69]
	s_cbranch_execz .LBB0_333
	buffer_wbl2 sc1
	s_waitcnt vmcnt(0)
	v_mov_b32_e32 v2, 0
	v_readlane_b32 s4, v255, 58
	v_readlane_b32 s5, v255, 59
	v_readlane_b32 s6, v255, 60
	v_readlane_b32 s7, v255, 61
	v_readlane_b32 vcc_hi, v255, 62
	s_nop 3
	v_mov_b32_e32 v0, s6
	v_readlane_b32 s6, v255, 2
	s_add_i32 s7, s7, 1
	v_writelane_b32 v255, s7, 61
	s_nop 3
	s_lshl_b32 s6, s6, 6
	s_add_i32 s6, s6, 0x1f80800
	v_mov_b32_e32 v1, s6
	v_mov_b32_e32 v3, 1
	global_atomic_add v3, v1, v3, s[90:91] sc0
	s_waitcnt vmcnt(0)
	v_readfirstlane_b32 s6, v0
	s_nop 3
	s_lshr_b32 vcc_lo, s6, 3
	s_mul_i32 s7, s7, vcc_lo
	v_readfirstlane_b32 s6, v3
	s_nop 3
	s_add_i32 s6, s6, 1
	s_cmp_eq_u32 s6, s7
	s_cbranch_scc0 .Lgb5_poll
	v_mov_b32_e32 v3, vcc_lo
	global_atomic_add v3, v2, v3, s[4:5] offset:32 sc0
	s_waitcnt vmcnt(0)
	v_readfirstlane_b32 s6, v3
	v_readfirstlane_b32 s7, v0
	s_nop 3
	s_and_b32 s6, s6, 0xffff
	s_add_i32 s6, s6, vcc_lo
	s_cmp_eq_u32 s6, s7
	s_cbranch_scc0 .Lgb5_poll
	s_sub_i32 s6, 0x10000, s7
	v_mov_b32_e32 v3, s6
	global_atomic_add v2, v3, s[4:5] offset:32

; __global__ void __launch_bounds__(512, 2) hymba_fwd(Params p) {
;     ...
;   phase_norm2(p);
;   grid.sync();
;   phase_up(p, lds);
.LBB0_342:
	s_or_b64 exec, exec, s[10:11]
	s_waitcnt lgkmcnt(0)
	s_barrier
	s_and_saveexec_b64 s[2:3], s[68:69]
	s_cbranch_execz .LBB0_352
	buffer_wbl2 sc1
	s_waitcnt vmcnt(0)
	v_mov_b32_e32 v2, 0
	v_readlane_b32 s4, v255, 58
	v_readlane_b32 s5, v255, 59
	v_readlane_b32 s6, v255, 60
	v_readlane_b32 s7, v255, 61
	v_readlane_b32 vcc_hi, v255, 62
	s_nop 3
	v_mov_b32_e32 v0, s6
	v_readlane_b32 s6, v255, 2
	s_add_i32 s7, s7, 1
	v_writelane_b32 v255, s7, 61
	s_nop 3
	s_lshl_b32 s6, s6, 6
	s_add_i32 s6, s6, 0x1f80800
	v_mov_b32_e32 v1, s6
	v_mov_b32_e32 v3, 1
	global_atomic_add v3, v1, v3, s[90:91] sc0
	s_waitcnt vmcnt(0)
	v_readfirstlane_b32 s6, v0
	s_nop 3
	s_lshr_b32 vcc_lo, s6, 3
	s_mul_i32 s7, s7, vcc_lo
	v_readfirstlane_b32 s6, v3
	s_nop 3
	s_add_i32 s6, s6, 1
	s_cmp_eq_u32 s6, s7
	s_cbranch_scc0 .Lgb6_poll
	v_mov_b32_e32 v3, vcc_lo
	global_atomic_add v3, v2, v3, s[4:5] offset:32 sc0
	s_waitcnt vmcnt(0)
	v_readfirstlane_b32 s6, v3
	v_readfirstlane_b32 s7, v0
	s_nop 3
	s_and_b32 s6, s6, 0xffff
	s_add_i32 s6, s6, vcc_lo
	s_cmp_eq_u32 s6, s7
	s_cbranch_scc0 .Lgb6_poll
	s_sub_i32 s6, 0x10000, s7
	v_mov_b32_e32 v3, s6
	global_atomic_add v2, v3, s[4:5] offset:32

; __global__ void __launch_bounds__(512, 2) hymba_fwd(Params p) {
;     ...
;   phase_down(p, lds);
;   grid.sync();
;   phase_final(p);
.LBB0_388:
	s_barrier
	s_and_saveexec_b64 s[0:1], s[68:69]
	s_cbranch_execz .LBB0_398
	buffer_wbl2 sc1
	s_waitcnt vmcnt(0)
	v_mov_b32_e32 v2, 0
	v_readlane_b32 s4, v255, 58
	v_readlane_b32 s5, v255, 59
	v_readlane_b32 s6, v255, 60
	v_readlane_b32 s7, v255, 61
	v_readlane_b32 vcc_hi, v255, 62
	s_nop 3
	v_mov_b32_e32 v0, s6
	v_readlane_b32 s6, v255, 2
	s_add_i32 s7, s7, 1
	v_writelane_b32 v255, s7, 61
	s_nop 3
	s_lshl_b32 s6, s6, 6
	s_add_i32 s6, s6, 0x1f80800
	v_mov_b32_e32 v1, s6
	v_mov_b32_e32 v3, 1
	global_atomic_add v3, v1, v3, s[90:91] sc0
	s_waitcnt vmcnt(0)
	v_readfirstlane_b32 s6, v0
	s_nop 3
	s_lshr_b32 vcc_lo, s6, 3
	s_mul_i32 s7, s7, vcc_lo
	v_readfirstlane_b32 s6, v3
	s_nop 3
	s_add_i32 s6, s6, 1
	s_cmp_eq_u32 s6, s7
	s_cbranch_scc0 .Lgb8_poll
	v_mov_b32_e32 v3, vcc_lo
	global_atomic_add v3, v2, v3, s[4:5] offset:32 sc0
	s_waitcnt vmcnt(0)
	v_readfirstlane_b32 s6, v3
	v_readfirstlane_b32 s7, v0
	s_nop 3
	s_and_b32 s6, s6, 0xffff
	s_add_i32 s6, s6, vcc_lo
	s_cmp_eq_u32 s6, s7
	s_cbranch_scc0 .Lgb8_poll
	s_sub_i32 s6, 0x10000, s7
	v_mov_b32_e32 v3, s6
	global_atomic_add v2, v3, s[4:5] offset:32
